# 64-byte alignment of the seven GEMM K-loop heads and the two attention tile-loop heads
# speedup vs baseline: 1.0083x; 1.0083x over previous
.LBB0_98:
	v_and_b32_e32 v0, 48, v134
	s_lshl_b32 s15, s15, 5
	v_lshlrev_b32_e32 v1, 6, v134
	s_movk_i32 s28, 0x3c0
	v_and_or_b32 v0, v1, s28, v0
	v_lshlrev_b32_e32 v1, 2, v134
	s_and_b32 s64, s15, 0x60
	s_lshl_b32 s63, s14, 6
	v_and_b32_e32 v1, 32, v1
	s_lshl_b32 s14, s14, 13
	s_lshl_b32 s15, s64, 7
	s_waitcnt vmcnt(8)
	s_barrier
	s_waitcnt vmcnt(6)
	v_bitop3_b32 v2, v0, s14, v1 bitop3:0xde
	v_bitop3_b32 v135, s15, v0, v1 bitop3:0xf6
	v_mov_b32_e32 v0, 0
	s_mov_b32 s34, 0
	s_mov_b64 s[14:15], -1
	s_mov_b64 s[28:29], 0
	v_add_u32_e32 v136, 0, v2
	v_mov_b32_e32 v1, v0
	v_mov_b32_e32 v2, v0
	v_mov_b32_e32 v3, v0
	v_mov_b32_e32 v4, v0
	v_mov_b32_e32 v5, v0
	v_mov_b32_e32 v6, v0
	v_mov_b32_e32 v7, v0
	v_mov_b32_e32 v8, v0
	v_mov_b32_e32 v9, v0
	v_mov_b32_e32 v10, v0
	v_mov_b32_e32 v11, v0
	v_mov_b32_e32 v16, v0
	v_mov_b32_e32 v17, v0
	v_mov_b32_e32 v18, v0
	v_mov_b32_e32 v19, v0
	v_mov_b32_e32 v24, v0
	v_mov_b32_e32 v25, v0
	v_mov_b32_e32 v26, v0
	v_mov_b32_e32 v27, v0
	v_mov_b32_e32 v32, v0
	v_mov_b32_e32 v33, v0
	v_mov_b32_e32 v34, v0
	v_mov_b32_e32 v35, v0
	v_mov_b32_e32 v40, v0
	v_mov_b32_e32 v41, v0
	v_mov_b32_e32 v42, v0
	v_mov_b32_e32 v43, v0
	v_mov_b32_e32 v48, v0
	v_mov_b32_e32 v49, v0
	v_mov_b32_e32 v50, v0
	v_mov_b32_e32 v51, v0
	v_mov_b32_e32 v12, v0
	v_mov_b32_e32 v13, v0
	v_mov_b32_e32 v14, v0
	v_mov_b32_e32 v15, v0
	v_mov_b32_e32 v20, v0
	v_mov_b32_e32 v21, v0
	v_mov_b32_e32 v22, v0
	v_mov_b32_e32 v23, v0
	v_mov_b32_e32 v28, v0
	v_mov_b32_e32 v29, v0
	v_mov_b32_e32 v30, v0
	v_mov_b32_e32 v31, v0
	v_mov_b32_e32 v36, v0
	v_mov_b32_e32 v37, v0
	v_mov_b32_e32 v38, v0
	v_mov_b32_e32 v39, v0
	v_mov_b32_e32 v44, v0
	v_mov_b32_e32 v45, v0
	v_mov_b32_e32 v46, v0
	v_mov_b32_e32 v47, v0
	v_mov_b32_e32 v52, v0
	v_mov_b32_e32 v53, v0
	v_mov_b32_e32 v54, v0
	v_mov_b32_e32 v55, v0
	v_mov_b32_e32 v56, v0
	v_mov_b32_e32 v57, v0
	v_mov_b32_e32 v58, v0
	v_mov_b32_e32 v59, v0
	v_mov_b32_e32 v60, v0
	v_mov_b32_e32 v61, v0
	v_mov_b32_e32 v62, v0
	v_mov_b32_e32 v63, v0
	v_mov_b32_e32 v64, v0
	v_mov_b32_e32 v65, v0
	v_mov_b32_e32 v66, v0
	v_mov_b32_e32 v67, v0
	v_mov_b32_e32 v68, v0
	v_mov_b32_e32 v69, v0
	v_mov_b32_e32 v70, v0
	v_mov_b32_e32 v71, v0
	v_mov_b32_e32 v72, v0
	v_mov_b32_e32 v73, v0
	v_mov_b32_e32 v74, v0
	v_mov_b32_e32 v75, v0
	v_mov_b32_e32 v80, v0
	v_mov_b32_e32 v81, v0
	v_mov_b32_e32 v82, v0
	v_mov_b32_e32 v83, v0
	v_mov_b32_e32 v88, v0
	v_mov_b32_e32 v89, v0
	v_mov_b32_e32 v90, v0
	v_mov_b32_e32 v91, v0
	v_mov_b32_e32 v96, v0
	v_mov_b32_e32 v97, v0
	v_mov_b32_e32 v98, v0
	v_mov_b32_e32 v99, v0
	v_mov_b32_e32 v104, v0
	v_mov_b32_e32 v105, v0
	v_mov_b32_e32 v106, v0
	v_mov_b32_e32 v107, v0
	v_mov_b32_e32 v112, v0
	v_mov_b32_e32 v113, v0
	v_mov_b32_e32 v114, v0
	v_mov_b32_e32 v115, v0
	v_mov_b32_e32 v76, v0
	v_mov_b32_e32 v77, v0
	v_mov_b32_e32 v78, v0
	v_mov_b32_e32 v79, v0
	v_mov_b32_e32 v84, v0
	v_mov_b32_e32 v85, v0
	v_mov_b32_e32 v86, v0
	v_mov_b32_e32 v87, v0
	v_mov_b32_e32 v92, v0
	v_mov_b32_e32 v93, v0
	v_mov_b32_e32 v94, v0
	v_mov_b32_e32 v95, v0
	v_mov_b32_e32 v100, v0
	v_mov_b32_e32 v101, v0
	v_mov_b32_e32 v102, v0
	v_mov_b32_e32 v103, v0
	v_mov_b32_e32 v108, v0
	v_mov_b32_e32 v109, v0
	v_mov_b32_e32 v110, v0
	v_mov_b32_e32 v111, v0
	v_mov_b32_e32 v116, v0
	v_mov_b32_e32 v117, v0
	v_mov_b32_e32 v118, v0
	v_mov_b32_e32 v119, v0
	v_mov_b32_e32 v120, v0
	v_mov_b32_e32 v121, v0
	v_mov_b32_e32 v122, v0
	v_mov_b32_e32 v123, v0
	v_mov_b32_e32 v124, v0
	v_mov_b32_e32 v125, v0
	v_mov_b32_e32 v126, v0
	v_mov_b32_e32 v127, v0
	s_barrier
	.p2align	6

.LBB0_105:
	v_and_b32_e32 v6, 48, v138
	s_lshl_b32 s5, s5, 5
	v_lshlrev_b32_e32 v7, 6, v138
	s_movk_i32 s28, 0x3c0
	s_lshr_b32 s9, s31, 1
	v_and_or_b32 v6, v7, s28, v6
	v_lshlrev_b32_e32 v7, 2, v138
	s_and_b32 s53, s5, 0x60
	s_and_b32 s9, s9, 7
	s_lshl_b32 s52, s4, 6
	v_and_b32_e32 v7, 32, v7
	s_lshl_b32 s4, s4, 13
	s_lshl_b32 s5, s53, 7
	s_lshl_b32 s9, s9, 18
	v_bitop3_b32 v8, v6, s4, v7 bitop3:0xde
	v_bitop3_b32 v139, s5, v6, v7 bitop3:0xf6
	v_lshlrev_b32_e32 v6, 13, v0
	s_add_u32 s2, s2, s9
	v_and_b32_e32 v6, 0xffffc000, v6
	s_addc_u32 s3, s3, 0
	v_lshl_add_u32 v1, v1, 10, v6
	v_and_b32_e32 v0, 1, v0
	v_readlane_b32 s4, v253, 38
	v_lshl_or_b32 v0, v0, 6, v1
	s_add_u32 s2, s4, s2
	v_readlane_b32 s4, v253, 39
	v_lshl_add_u32 v0, v2, 1, v0
	v_mov_b32_e32 v1, v193
	s_addc_u32 s3, s4, s3
	v_lshl_add_u64 v[134:135], s[2:3], 0, v[0:1]
	v_lshlrev_b32_e32 v0, 13, v3
	v_and_b32_e32 v0, 0xffffc000, v0
	v_lshl_add_u32 v0, v4, 10, v0
	v_and_b32_e32 v1, 1, v3
	v_lshl_or_b32 v0, v1, 6, v0
	s_waitcnt vmcnt(8)
	s_barrier
	s_waitcnt vmcnt(6)
	v_lshl_add_u32 v0, v5, 1, v0
	v_mov_b32_e32 v1, v193
	v_lshl_add_u64 v[136:137], s[2:3], 0, v[0:1]
	v_mov_b32_e32 v0, 0
	s_mov_b32 s54, -2
	s_mov_b64 s[2:3], 0
	v_add_u32_e32 v140, 0, v8
	v_mov_b32_e32 v1, v0
	v_mov_b32_e32 v2, v0
	v_mov_b32_e32 v3, v0
	v_mov_b32_e32 v4, v0
	v_mov_b32_e32 v5, v0
	v_mov_b32_e32 v6, v0
	v_mov_b32_e32 v7, v0
	v_mov_b32_e32 v8, v0
	v_mov_b32_e32 v9, v0
	v_mov_b32_e32 v10, v0
	v_mov_b32_e32 v11, v0
	v_mov_b32_e32 v16, v0
	v_mov_b32_e32 v17, v0
	v_mov_b32_e32 v18, v0
	v_mov_b32_e32 v19, v0
	v_mov_b32_e32 v24, v0
	v_mov_b32_e32 v25, v0
	v_mov_b32_e32 v26, v0
	v_mov_b32_e32 v27, v0
	v_mov_b32_e32 v32, v0
	v_mov_b32_e32 v33, v0
	v_mov_b32_e32 v34, v0
	v_mov_b32_e32 v35, v0
	v_mov_b32_e32 v40, v0
	v_mov_b32_e32 v41, v0
	v_mov_b32_e32 v42, v0
	v_mov_b32_e32 v43, v0
	v_mov_b32_e32 v48, v0
	v_mov_b32_e32 v49, v0
	v_mov_b32_e32 v50, v0
	v_mov_b32_e32 v51, v0
	v_mov_b32_e32 v12, v0
	v_mov_b32_e32 v13, v0
	v_mov_b32_e32 v14, v0
	v_mov_b32_e32 v15, v0
	v_mov_b32_e32 v20, v0
	v_mov_b32_e32 v21, v0
	v_mov_b32_e32 v22, v0
	v_mov_b32_e32 v23, v0
	v_mov_b32_e32 v28, v0
	v_mov_b32_e32 v29, v0
	v_mov_b32_e32 v30, v0
	v_mov_b32_e32 v31, v0
	v_mov_b32_e32 v36, v0
	v_mov_b32_e32 v37, v0
	v_mov_b32_e32 v38, v0
	v_mov_b32_e32 v39, v0
	v_mov_b32_e32 v44, v0
	v_mov_b32_e32 v45, v0
	v_mov_b32_e32 v46, v0
	v_mov_b32_e32 v47, v0
	v_mov_b32_e32 v52, v0
	v_mov_b32_e32 v53, v0
	v_mov_b32_e32 v54, v0
	v_mov_b32_e32 v55, v0
	v_mov_b32_e32 v56, v0
	v_mov_b32_e32 v57, v0
	v_mov_b32_e32 v58, v0
	v_mov_b32_e32 v59, v0
	v_mov_b32_e32 v60, v0
	v_mov_b32_e32 v61, v0
	v_mov_b32_e32 v62, v0
	v_mov_b32_e32 v63, v0
	v_mov_b32_e32 v64, v0
	v_mov_b32_e32 v65, v0
	v_mov_b32_e32 v66, v0
	v_mov_b32_e32 v67, v0
	v_mov_b32_e32 v68, v0
	v_mov_b32_e32 v69, v0
	v_mov_b32_e32 v70, v0
	v_mov_b32_e32 v71, v0
	v_mov_b32_e32 v72, v0
	v_mov_b32_e32 v73, v0
	v_mov_b32_e32 v74, v0
	v_mov_b32_e32 v75, v0
	v_mov_b32_e32 v80, v0
	v_mov_b32_e32 v81, v0
	v_mov_b32_e32 v82, v0
	v_mov_b32_e32 v83, v0
	v_mov_b32_e32 v88, v0
	v_mov_b32_e32 v89, v0
	v_mov_b32_e32 v90, v0
	v_mov_b32_e32 v91, v0
	v_mov_b32_e32 v96, v0
	v_mov_b32_e32 v97, v0
	v_mov_b32_e32 v98, v0
	v_mov_b32_e32 v99, v0
	v_mov_b32_e32 v104, v0
	v_mov_b32_e32 v105, v0
	v_mov_b32_e32 v106, v0
	v_mov_b32_e32 v107, v0
	v_mov_b32_e32 v112, v0
	v_mov_b32_e32 v113, v0
	v_mov_b32_e32 v114, v0
	v_mov_b32_e32 v115, v0
	v_mov_b32_e32 v76, v0
	v_mov_b32_e32 v77, v0
	v_mov_b32_e32 v78, v0
	v_mov_b32_e32 v79, v0
	v_mov_b32_e32 v84, v0
	v_mov_b32_e32 v85, v0
	v_mov_b32_e32 v86, v0
	v_mov_b32_e32 v87, v0
	v_mov_b32_e32 v92, v0
	v_mov_b32_e32 v93, v0
	v_mov_b32_e32 v94, v0
	v_mov_b32_e32 v95, v0
	v_mov_b32_e32 v100, v0
	v_mov_b32_e32 v101, v0
	v_mov_b32_e32 v102, v0
	v_mov_b32_e32 v103, v0
	v_mov_b32_e32 v108, v0
	v_mov_b32_e32 v109, v0
	v_mov_b32_e32 v110, v0
	v_mov_b32_e32 v111, v0
	v_mov_b32_e32 v116, v0
	v_mov_b32_e32 v117, v0
	v_mov_b32_e32 v118, v0
	v_mov_b32_e32 v119, v0
	v_mov_b32_e32 v120, v0
	v_mov_b32_e32 v121, v0
	v_mov_b32_e32 v122, v0
	v_mov_b32_e32 v123, v0
	v_mov_b32_e32 v124, v0
	v_mov_b32_e32 v125, v0
	v_mov_b32_e32 v126, v0
	v_mov_b32_e32 v127, v0
	s_barrier
	.p2align	6

.LBB0_131:
	s_add_i32 s64, s63, -2
	s_add_u32 s2, s2, 0x80080
	s_addc_u32 s3, s3, 0
	s_add_u32 s67, s4, 0x100
	v_mov_b32_e32 v0, 0
	s_addc_u32 s69, s5, 0
	s_mov_b32 s4, 0
	v_mov_b32_e32 v1, v0
	v_mov_b32_e32 v2, v0
	v_mov_b32_e32 v3, v0
	v_mov_b32_e32 v4, v0
	v_mov_b32_e32 v5, v0
	v_mov_b32_e32 v6, v0
	v_mov_b32_e32 v7, v0
	v_mov_b32_e32 v8, v0
	v_mov_b32_e32 v9, v0
	v_mov_b32_e32 v10, v0
	v_mov_b32_e32 v11, v0
	v_mov_b32_e32 v16, v0
	v_mov_b32_e32 v17, v0
	v_mov_b32_e32 v18, v0
	v_mov_b32_e32 v19, v0
	v_mov_b32_e32 v24, v0
	v_mov_b32_e32 v25, v0
	v_mov_b32_e32 v26, v0
	v_mov_b32_e32 v27, v0
	v_mov_b32_e32 v32, v0
	v_mov_b32_e32 v33, v0
	v_mov_b32_e32 v34, v0
	v_mov_b32_e32 v35, v0
	v_mov_b32_e32 v40, v0
	v_mov_b32_e32 v41, v0
	v_mov_b32_e32 v42, v0
	v_mov_b32_e32 v43, v0
	v_mov_b32_e32 v48, v0
	v_mov_b32_e32 v49, v0
	v_mov_b32_e32 v50, v0
	v_mov_b32_e32 v51, v0
	v_mov_b32_e32 v12, v0
	v_mov_b32_e32 v13, v0
	v_mov_b32_e32 v14, v0
	v_mov_b32_e32 v15, v0
	v_mov_b32_e32 v20, v0
	v_mov_b32_e32 v21, v0
	v_mov_b32_e32 v22, v0
	v_mov_b32_e32 v23, v0
	v_mov_b32_e32 v28, v0
	v_mov_b32_e32 v29, v0
	v_mov_b32_e32 v30, v0
	v_mov_b32_e32 v31, v0
	v_mov_b32_e32 v36, v0
	v_mov_b32_e32 v37, v0
	v_mov_b32_e32 v38, v0
	v_mov_b32_e32 v39, v0
	v_mov_b32_e32 v44, v0
	v_mov_b32_e32 v45, v0
	v_mov_b32_e32 v46, v0
	v_mov_b32_e32 v47, v0
	v_mov_b32_e32 v52, v0
	v_mov_b32_e32 v53, v0
	v_mov_b32_e32 v54, v0
	v_mov_b32_e32 v55, v0
	v_mov_b32_e32 v56, v0
	v_mov_b32_e32 v57, v0
	v_mov_b32_e32 v58, v0
	v_mov_b32_e32 v59, v0
	v_mov_b32_e32 v60, v0
	v_mov_b32_e32 v61, v0
	v_mov_b32_e32 v62, v0
	v_mov_b32_e32 v63, v0
	v_mov_b32_e32 v64, v0
	v_mov_b32_e32 v65, v0
	v_mov_b32_e32 v66, v0
	v_mov_b32_e32 v67, v0
	v_mov_b32_e32 v68, v0
	v_mov_b32_e32 v69, v0
	v_mov_b32_e32 v70, v0
	v_mov_b32_e32 v71, v0
	v_mov_b32_e32 v72, v0
	v_mov_b32_e32 v73, v0
	v_mov_b32_e32 v74, v0
	v_mov_b32_e32 v75, v0
	v_mov_b32_e32 v80, v0
	v_mov_b32_e32 v81, v0
	v_mov_b32_e32 v82, v0
	v_mov_b32_e32 v83, v0
	v_mov_b32_e32 v88, v0
	v_mov_b32_e32 v89, v0
	v_mov_b32_e32 v90, v0
	v_mov_b32_e32 v91, v0
	v_mov_b32_e32 v96, v0
	v_mov_b32_e32 v97, v0
	v_mov_b32_e32 v98, v0
	v_mov_b32_e32 v99, v0
	v_mov_b32_e32 v104, v0
	v_mov_b32_e32 v105, v0
	v_mov_b32_e32 v106, v0
	v_mov_b32_e32 v107, v0
	v_mov_b32_e32 v112, v0
	v_mov_b32_e32 v113, v0
	v_mov_b32_e32 v114, v0
	v_mov_b32_e32 v115, v0
	v_mov_b32_e32 v76, v0
	v_mov_b32_e32 v77, v0
	v_mov_b32_e32 v78, v0
	v_mov_b32_e32 v79, v0
	v_mov_b32_e32 v84, v0
	v_mov_b32_e32 v85, v0
	v_mov_b32_e32 v86, v0
	v_mov_b32_e32 v87, v0
	v_mov_b32_e32 v92, v0
	v_mov_b32_e32 v93, v0
	v_mov_b32_e32 v94, v0
	v_mov_b32_e32 v95, v0
	v_mov_b32_e32 v100, v0
	v_mov_b32_e32 v101, v0
	v_mov_b32_e32 v102, v0
	v_mov_b32_e32 v103, v0
	v_mov_b32_e32 v108, v0
	v_mov_b32_e32 v109, v0
	v_mov_b32_e32 v110, v0
	v_mov_b32_e32 v111, v0
	v_mov_b32_e32 v116, v0
	v_mov_b32_e32 v117, v0
	v_mov_b32_e32 v118, v0
	v_mov_b32_e32 v119, v0
	v_mov_b32_e32 v120, v0
	v_mov_b32_e32 v121, v0
	v_mov_b32_e32 v122, v0
	v_mov_b32_e32 v123, v0
	v_mov_b32_e32 v124, v0
	v_mov_b32_e32 v125, v0
	v_mov_b32_e32 v126, v0
	v_mov_b32_e32 v127, v0
	.p2align	6

.LBB0_181:
	v_mov_b32_e32 v20, v224
	s_ashr_i32 s0, s31, 1
	s_lshl_b32 s2, s31, 7
	v_readfirstlane_b32 s58, v20
	s_bfe_u32 s59, s58, 0x20006
	s_lshl_b32 s1, s0, 8
	s_and_b32 s2, s2, 0x80
	s_or_b32 s1, s1, s2
	s_lshl_b32 s2, s59, 5
	s_or_b32 s1, s1, s2
	v_and_b32_e32 v21, 31, v20
	s_addk_i32 s1, 0x2000
	s_ashr_i32 s64, s58, 8
	v_or_b32_e32 v192, s1, v21
	v_lshlrev_b64 v[0:1], 11, v[192:193]
	s_lshl_b32 s2, s64, 6
	v_bfe_u32 v163, v20, 5, 1
	v_lshl_add_u64 v[0:1], s[34:35], 0, v[0:1]
	s_ashr_i32 s3, s2, 31
	v_lshl_add_u64 v[0:1], s[2:3], 1, v[0:1]
	v_lshlrev_b32_e32 v160, 4, v163
	v_mov_b32_e32 v161, v193
	v_lshl_add_u64 v[0:1], v[0:1], 0, v[160:161]
	global_load_dwordx4 v[112:115], v[0:1], off
	global_load_dwordx4 v[116:119], v[0:1], off offset:32
	global_load_dwordx4 v[120:123], v[0:1], off offset:64
	s_lshl_b32 s1, s0, 3
	global_load_dwordx4 v[124:127], v[0:1], off offset:96
	s_or_b32 s1, s1, s54
	s_lshl_b32 s2, s1, 1
	s_mul_i32 s4, s1, 0x90000
	s_mul_hi_i32 s3, s2, 0x48000
	s_add_u32 s2, s56, s4
	s_addc_u32 s3, s57, s3
	s_mul_hi_i32 s1, s1, 0x90000
	s_add_u32 s48, s44, s4
	s_addc_u32 s49, s45, s1
	s_add_u32 s62, s2, 0x48000
	s_addc_u32 s63, s3, 0
	s_add_u32 s4, s48, 0x48000
	s_addc_u32 s5, s49, 0
	s_lshl_b32 s0, s0, 4
	s_add_i32 s0, s0, s75
	s_add_i32 s0, s0, s64
	s_ashr_i32 s1, s0, 31
	v_ashrrev_i32_e32 v2, 3, v20
	v_and_b32_e32 v3, 7, v20
	s_lshl_b64 s[0:1], s[0:1], 2
	v_readlane_b32 s9, v252, 46
	v_lshlrev_b32_e32 v164, 7, v2
	v_lshlrev_b32_e32 v3, 4, v3
	s_add_u32 s0, s9, s0
	v_readlane_b32 s9, v252, 47
	v_or_b32_e32 v26, v164, v3
	s_addc_u32 s1, s9, s1
	global_load_dwordx4 v[128:131], v26, s[2:3]
	global_load_dwordx4 v[132:135], v26, s[62:63]
	global_load_dword v27, v193, s[0:1]
	v_mul_lo_u32 v2, v2, s7
	v_or_b32_e32 v166, v2, v3
	v_lshrrev_b32_e32 v22, 4, v20
	v_and_b32_e32 v24, 6, v20
	v_bfe_u32 v23, v20, 4, 3
	v_bitop3_b32 v25, v22, v20, 7 bitop3:0x28
	v_lshl_or_b32 v169, v25, 4, v164
	v_lshlrev_b32_e32 v21, 7, v21
	v_mov_b32_e32 v167, 0
	v_mov_b32_e32 v148, 0
	v_and_b32_e32 v165, 63, v20
	s_mov_b32 s71, 0
	v_add_u32_e32 v173, 0, v21
	v_add_u32_e32 v177, 0x4000, v26
	s_mov_b32 s31, 0
	v_mov_b32_e32 v149, v148
	v_mov_b32_e32 v150, v148
	v_mov_b32_e32 v151, v148
	v_mov_b32_e32 v144, v148
	v_mov_b32_e32 v145, v148
	v_mov_b32_e32 v146, v148
	v_mov_b32_e32 v147, v148
	v_mov_b32_e32 v140, v148
	v_mov_b32_e32 v141, v148
	v_mov_b32_e32 v142, v148
	v_mov_b32_e32 v143, v148
	v_mov_b32_e32 v136, v148
	v_mov_b32_e32 v137, v148
	v_mov_b32_e32 v138, v148
	v_mov_b32_e32 v139, v148
	v_mov_b32_e32 v48, 0
	v_mov_b32_e32 v49, v167
	v_mov_b32_e32 v50, v167
	v_mov_b32_e32 v51, v167
	v_mov_b32_e32 v52, v167
	v_mov_b32_e32 v53, v167
	v_mov_b32_e32 v54, v167
	v_mov_b32_e32 v55, v167
	v_mov_b32_e32 v56, v167
	v_mov_b32_e32 v57, v167
	v_mov_b32_e32 v58, v167
	v_mov_b32_e32 v59, v167
	v_mov_b32_e32 v60, v167
	v_mov_b32_e32 v61, v167
	v_mov_b32_e32 v62, v167
	v_mov_b32_e32 v63, v167
	s_waitcnt vmcnt(6)
	v_and_b32_e32 v1, 0xffff0000, v112
	v_and_b32_e32 v3, 0xffff0000, v113
	v_lshlrev_b32_e32 v0, 16, v112
	v_lshlrev_b32_e32 v2, 16, v113
	v_and_b32_e32 v5, 0xffff0000, v114
	v_mul_f32_e32 v1, v1, v1
	v_mul_f32_e32 v3, v3, v3
	v_lshlrev_b32_e32 v4, 16, v114
	v_and_b32_e32 v7, 0xffff0000, v115
	v_mul_f32_e32 v5, v5, v5
	v_fmac_f32_e32 v1, v0, v0
	v_fmac_f32_e32 v3, v2, v2
	v_lshlrev_b32_e32 v6, 16, v115
	s_waitcnt vmcnt(5)
	v_and_b32_e32 v9, 0xffff0000, v116
	v_mul_f32_e32 v7, v7, v7
	v_fmac_f32_e32 v5, v4, v4
	v_add_f32_e32 v0, v1, v3
	v_lshlrev_b32_e32 v8, 16, v116
	v_and_b32_e32 v11, 0xffff0000, v117
	v_mul_f32_e32 v9, v9, v9
	v_fmac_f32_e32 v7, v6, v6
	v_add_f32_e32 v0, v5, v0
	v_lshlrev_b32_e32 v10, 16, v117
	v_and_b32_e32 v13, 0xffff0000, v118
	v_mul_f32_e32 v11, v11, v11
	v_fmac_f32_e32 v9, v8, v8
	v_add_f32_e32 v0, v7, v0
	v_lshlrev_b32_e32 v12, 16, v118
	v_and_b32_e32 v15, 0xffff0000, v119
	v_mul_f32_e32 v13, v13, v13
	v_fmac_f32_e32 v11, v10, v10
	v_add_f32_e32 v0, v9, v0
	v_lshlrev_b32_e32 v14, 16, v119
	v_mul_f32_e32 v15, v15, v15
	v_fmac_f32_e32 v13, v12, v12
	v_add_f32_e32 v0, v11, v0
	v_fmac_f32_e32 v15, v14, v14
	v_add_f32_e32 v0, v13, v0
	v_add_f32_e32 v16, v15, v0
	global_load_dwordx4 v[0:3], v166, s[48:49]
	v_add_u32_e32 v12, 0x2000, v26
	global_load_dwordx4 v[4:7], v166, s[4:5]
	global_load_dwordx4 v[8:11], v12, s[2:3]
	s_nop 0
	global_load_dwordx4 v[12:15], v12, s[62:63]
	s_waitcnt vmcnt(8)
	v_and_b32_e32 v18, 0xffff0000, v120
	v_lshlrev_b32_e32 v17, 16, v120
	v_mul_f32_e32 v18, v18, v18
	v_fmac_f32_e32 v18, v17, v17
	v_add_f32_e32 v16, v18, v16
	v_and_b32_e32 v18, 0xffff0000, v121
	v_lshlrev_b32_e32 v17, 16, v121
	v_mul_f32_e32 v18, v18, v18
	v_fmac_f32_e32 v18, v17, v17
	v_add_f32_e32 v28, v18, v16
	v_and_b32_e32 v19, 0xffff0000, v123
	v_and_b32_e32 v18, 0xffff0000, v122
	v_lshlrev_b32_e32 v17, 16, v123
	v_lshlrev_b32_e32 v16, 16, v122
	v_pk_mul_f32 v[18:19], v[18:19], v[18:19]
	v_mov_b32_e32 v32, 0
	v_pk_fma_f32 v[16:17], v[16:17], v[16:17], v[18:19]
	s_waitcnt vmcnt(7)
	v_and_b32_e32 v19, 0xffff0000, v125
	v_add_f32_e32 v16, v16, v28
	v_and_b32_e32 v18, 0xffff0000, v124
	v_add_f32_e32 v28, v17, v16
	v_lshlrev_b32_e32 v17, 16, v125
	v_lshlrev_b32_e32 v16, 16, v124
	v_pk_mul_f32 v[18:19], v[18:19], v[18:19]
	v_mov_b32_e32 v33, v167
	v_pk_fma_f32 v[16:17], v[16:17], v[16:17], v[18:19]
	v_and_b32_e32 v19, 0xffff0000, v127
	v_add_f32_e32 v16, v16, v28
	v_and_b32_e32 v18, 0xffff0000, v126
	v_add_f32_e32 v28, v17, v16
	v_lshlrev_b32_e32 v17, 16, v127
	v_lshlrev_b32_e32 v16, 16, v126
	v_pk_mul_f32 v[18:19], v[18:19], v[18:19]
	v_mov_b32_e32 v34, v167
	v_pk_fma_f32 v[16:17], v[16:17], v[16:17], v[18:19]
	v_and_b32_e32 v18, 64, v229
	v_add_f32_e32 v16, v16, v28
	v_add_f32_e32 v16, v17, v16
	v_xor_b32_e32 v17, 32, v229
	v_add_u32_e32 v18, 64, v18
	v_cmp_lt_i32_e32 vcc, v17, v18
	v_lshlrev_b32_e32 v19, 3, v20
	v_bitop3_b32 v18, v22, v24, 7 bitop3:0x6c
	v_cndmask_b32_e32 v17, v229, v17, vcc
	v_lshlrev_b32_e32 v161, 2, v17
	ds_bpermute_b32 v17, v161, v16
	v_and_b32_e32 v19, 8, v19
	v_bitop3_b32 v22, v24, v23, 1 bitop3:0x36
	v_lshl_or_b32 v171, v18, 4, v19
	v_lshl_or_b32 v168, v22, 4, v19
	s_waitcnt lgkmcnt(0)
	v_add_f32_e32 v16, v16, v17
	s_waitcnt vmcnt(4)
	v_mul_f32_e32 v16, v27, v16
	v_mul_f32_e32 v17, 0x4f800000, v16
	v_cmp_gt_f32_e32 vcc, s92, v16
	v_mov_b32_e32 v35, v167
	v_mov_b32_e32 v36, v167
	v_cndmask_b32_e32 v16, v16, v17, vcc
	v_sqrt_f32_e32 v17, v16
	v_mov_b32_e32 v37, v167
	v_mov_b32_e32 v38, v167
	v_mov_b32_e32 v39, v167
	v_add_u32_e32 v18, -1, v17
	v_fma_f32 v19, -v18, v17, v16
	v_cmp_ge_f32_e64 s[0:1], 0, v19
	v_add_u32_e32 v19, 1, v17
	v_mov_b32_e32 v40, v167
	v_cndmask_b32_e64 v18, v17, v18, s[0:1]
	v_fma_f32 v17, -v19, v17, v16
	v_cmp_lt_f32_e64 s[0:1], 0, v17
	v_mov_b32_e32 v41, v167
	v_mov_b32_e32 v42, v167
	v_cndmask_b32_e64 v17, v18, v19, s[0:1]
	v_mul_f32_e32 v18, 0x37800000, v17
	v_cndmask_b32_e32 v17, v17, v18, vcc
	v_cmp_class_f32_e32 vcc, v16, v228
	v_add_u32_e32 v18, 0, v164
	v_add_u32_e32 v19, v18, v171
	v_cndmask_b32_e32 v16, v17, v16, vcc
	v_fmamk_f32 v16, v16, 0x3f828f5c, v227
	v_add_u32_e32 v17, 0, v169
	v_xor_b32_e32 v64, 0x80000000, v16
	v_lshrrev_b32_e32 v16, 1, v20
	s_lshl_b32 s0, s64, 13
	ds_write_b128 v17, v[128:131]
	ds_write_b128 v17, v[132:135] offset:8192
	s_waitcnt vmcnt(3)
	ds_write_b64 v19, v[0:1] offset:49152
	v_add_u32_e32 v0, v18, v168
	s_waitcnt vmcnt(2)
	ds_write_b64 v19, v[4:5] offset:57344
	ds_write2st64_b64 v0, v[2:3], v[6:7] offset0:96 offset1:112
	s_waitcnt vmcnt(1)
	ds_write_b128 v17, v[8:11] offset:16384
	s_waitcnt vmcnt(0)
	ds_write_b128 v17, v[12:15] offset:24576
	s_add_i32 s0, s0, 0
	v_bitop3_b32 v0, v163, v16, 7 bitop3:0x78
	v_add_u32_e32 v176, s0, v21
	v_lshlrev_b32_e32 v175, 4, v0
	v_add_u32_e32 v4, v176, v175
	s_waitcnt lgkmcnt(0)
	s_barrier
	ds_read_b128 v[0:3], v4
	ds_read_b128 v[4:7], v4 offset:4096
	v_mov_b32_e32 v65, v64
	v_mov_b32_e32 v66, v64
	v_mov_b32_e32 v67, v64
	v_mov_b32_e32 v68, v64
	v_mov_b32_e32 v69, v64
	v_mov_b32_e32 v70, v64
	v_mov_b32_e32 v71, v64
	v_mov_b32_e32 v72, v64
	v_mov_b32_e32 v73, v64
	v_mov_b32_e32 v74, v64
	v_mov_b32_e32 v75, v64
	v_mov_b32_e32 v76, v64
	v_mov_b32_e32 v77, v64
	v_mov_b32_e32 v78, v64
	v_mov_b32_e32 v79, v64
	v_bfe_u32 v16, v20, 1, 3
	v_mov_b32_e32 v43, v167
	s_waitcnt lgkmcnt(1)
	v_mfma_f32_32x32x16_bf16 v[96:111], v[0:3], v[112:115], v[64:79]
	v_bitop3_b32 v0, v163, v16, 2 bitop3:0x36
	v_lshlrev_b32_e32 v174, 4, v0
	v_add_u32_e32 v8, v176, v174
	ds_read_b128 v[0:3], v8
	ds_read_b128 v[8:11], v8 offset:4096
	v_mov_b32_e32 v44, v167
	v_mov_b32_e32 v45, v167
	v_mov_b32_e32 v46, v167
	s_waitcnt lgkmcnt(2)
	v_mfma_f32_32x32x16_bf16 v[80:95], v[4:7], v[112:115], v[64:79]
	v_mov_b32_e32 v47, v167
	v_mov_b32_e32 v20, v167
	v_mov_b32_e32 v21, v167
	v_mov_b32_e32 v22, v167
	v_mov_b32_e32 v23, v167
	v_mov_b32_e32 v24, v167
	v_mov_b32_e32 v25, v167
	s_waitcnt lgkmcnt(1)
	v_mfma_f32_32x32x16_bf16 v[96:111], v[0:3], v[116:119], v[96:111]
	v_bitop3_b32 v0, v163, v16, 4 bitop3:0x36
	v_lshlrev_b32_e32 v172, 4, v0
	v_add_u32_e32 v12, v176, v172
	ds_read_b128 v[0:3], v12
	ds_read_b128 v[12:15], v12 offset:4096
	v_mov_b32_e32 v26, v167
	v_mov_b32_e32 v27, v167
	v_mov_b32_e32 v28, v167
	s_waitcnt lgkmcnt(2)
	v_mfma_f32_32x32x16_bf16 v[80:95], v[8:11], v[116:119], v[80:95]
	v_mov_b32_e32 v29, v167
	v_mov_b32_e32 v30, v167
	v_mov_b32_e32 v31, v167
	v_mov_b32_e32 v4, v167
	v_mov_b32_e32 v5, v167
	v_mov_b32_e32 v6, v167
	v_mov_b32_e32 v7, v167
	s_waitcnt lgkmcnt(1)
	v_mfma_f32_32x32x16_bf16 v[96:111], v[0:3], v[120:123], v[96:111]
	v_bitop3_b32 v0, v163, v16, 6 bitop3:0x36
	v_lshlrev_b32_e32 v170, 4, v0
	v_add_u32_e32 v16, v176, v170
	ds_read_b128 v[0:3], v16
	ds_read_b128 v[16:19], v16 offset:4096
	v_mov_b32_e32 v8, v167
	v_mov_b32_e32 v9, v167
	v_mov_b32_e32 v10, v167
	s_waitcnt lgkmcnt(2)
	v_mfma_f32_32x32x16_bf16 v[80:95], v[12:15], v[120:123], v[80:95]
	v_mov_b32_e32 v11, v167
	v_mov_b32_e32 v12, v167
	v_mov_b32_e32 v13, v167
	v_mov_b32_e32 v14, v167
	v_mov_b32_e32 v15, v167
	s_waitcnt lgkmcnt(1)
	v_mfma_f32_32x32x16_bf16 v[96:111], v[0:3], v[124:127], v[96:111]
	v_mov_b32_e32 v0, 0
	v_mov_b32_e32 v1, v167
	v_mov_b32_e32 v2, v167
	v_mov_b32_e32 v3, v167
	s_waitcnt lgkmcnt(0)
	v_mfma_f32_32x32x16_bf16 v[80:95], v[16:19], v[124:127], v[80:95]
	v_mov_b32_e32 v16, 0
	v_mov_b32_e32 v17, v167
	v_mov_b32_e32 v18, v167
	v_mov_b32_e32 v19, v167
	.p2align	6

.LBB0_197:
	v_and_b32_e32 v6, 48, v138
	s_lshl_b32 s0, s0, 5
	v_lshlrev_b32_e32 v7, 6, v138
	s_movk_i32 s2, 0x3c0
	v_and_or_b32 v6, v7, s2, v6
	v_lshlrev_b32_e32 v7, 2, v138
	s_and_b32 s74, s0, 0x60
	s_lshl_b32 s71, s1, 6
	v_and_b32_e32 v7, 32, v7
	s_lshl_b32 s1, s1, 13
	s_lshl_b32 s0, s74, 7
	v_bitop3_b32 v8, v6, s1, v7 bitop3:0xde
	v_bitop3_b32 v139, s0, v6, v7 bitop3:0xf6
	v_lshlrev_b32_e32 v6, 13, v0
	v_and_b32_e32 v6, 0xffffc000, v6
	v_lshl_add_u32 v1, v1, 10, v6
	v_and_b32_e32 v0, 1, v0
	v_lshl_or_b32 v0, v0, 6, v1
	v_lshl_add_u32 v0, v2, 1, v0
	v_mov_b32_e32 v1, v193
	v_lshl_add_u64 v[134:135], s[26:27], 0, v[0:1]
	v_lshlrev_b32_e32 v0, 13, v3
	v_and_b32_e32 v0, 0xffffc000, v0
	v_lshl_add_u32 v0, v4, 10, v0
	v_and_b32_e32 v1, 1, v3
	v_lshl_or_b32 v0, v1, 6, v0
	s_waitcnt vmcnt(8)
	s_barrier
	s_waitcnt vmcnt(6)
	v_lshl_add_u32 v0, v5, 1, v0
	v_mov_b32_e32 v1, v193
	v_lshl_add_u64 v[136:137], s[26:27], 0, v[0:1]
	v_mov_b32_e32 v0, 0
	v_mov_b32_e32 v129, v193
	v_mov_b32_e32 v131, v193
	s_mov_b32 vcc_lo, -2
	s_mov_b64 s[0:1], 0xd320080
	v_add_u32_e32 v140, 0, v8
	v_mov_b32_e32 v1, v0
	v_mov_b32_e32 v2, v0
	v_mov_b32_e32 v3, v0
	v_mov_b32_e32 v4, v0
	v_mov_b32_e32 v5, v0
	v_mov_b32_e32 v6, v0
	v_mov_b32_e32 v7, v0
	v_mov_b32_e32 v8, v0
	v_mov_b32_e32 v9, v0
	v_mov_b32_e32 v10, v0
	v_mov_b32_e32 v11, v0
	v_mov_b32_e32 v16, v0
	v_mov_b32_e32 v17, v0
	v_mov_b32_e32 v18, v0
	v_mov_b32_e32 v19, v0
	v_mov_b32_e32 v24, v0
	v_mov_b32_e32 v25, v0
	v_mov_b32_e32 v26, v0
	v_mov_b32_e32 v27, v0
	v_mov_b32_e32 v32, v0
	v_mov_b32_e32 v33, v0
	v_mov_b32_e32 v34, v0
	v_mov_b32_e32 v35, v0
	v_mov_b32_e32 v40, v0
	v_mov_b32_e32 v41, v0
	v_mov_b32_e32 v42, v0
	v_mov_b32_e32 v43, v0
	v_mov_b32_e32 v48, v0
	v_mov_b32_e32 v49, v0
	v_mov_b32_e32 v50, v0
	v_mov_b32_e32 v51, v0
	v_mov_b32_e32 v12, v0
	v_mov_b32_e32 v13, v0
	v_mov_b32_e32 v14, v0
	v_mov_b32_e32 v15, v0
	v_mov_b32_e32 v20, v0
	v_mov_b32_e32 v21, v0
	v_mov_b32_e32 v22, v0
	v_mov_b32_e32 v23, v0
	v_mov_b32_e32 v28, v0
	v_mov_b32_e32 v29, v0
	v_mov_b32_e32 v30, v0
	v_mov_b32_e32 v31, v0
	v_mov_b32_e32 v36, v0
	v_mov_b32_e32 v37, v0
	v_mov_b32_e32 v38, v0
	v_mov_b32_e32 v39, v0
	v_mov_b32_e32 v44, v0
	v_mov_b32_e32 v45, v0
	v_mov_b32_e32 v46, v0
	v_mov_b32_e32 v47, v0
	v_mov_b32_e32 v52, v0
	v_mov_b32_e32 v53, v0
	v_mov_b32_e32 v54, v0
	v_mov_b32_e32 v55, v0
	v_mov_b32_e32 v56, v0
	v_mov_b32_e32 v57, v0
	v_mov_b32_e32 v58, v0
	v_mov_b32_e32 v59, v0
	v_mov_b32_e32 v60, v0
	v_mov_b32_e32 v61, v0
	v_mov_b32_e32 v62, v0
	v_mov_b32_e32 v63, v0
	v_mov_b32_e32 v64, v0
	v_mov_b32_e32 v65, v0
	v_mov_b32_e32 v66, v0
	v_mov_b32_e32 v67, v0
	v_mov_b32_e32 v68, v0
	v_mov_b32_e32 v69, v0
	v_mov_b32_e32 v70, v0
	v_mov_b32_e32 v71, v0
	v_mov_b32_e32 v72, v0
	v_mov_b32_e32 v73, v0
	v_mov_b32_e32 v74, v0
	v_mov_b32_e32 v75, v0
	v_mov_b32_e32 v80, v0
	v_mov_b32_e32 v81, v0
	v_mov_b32_e32 v82, v0
	v_mov_b32_e32 v83, v0
	v_mov_b32_e32 v88, v0
	v_mov_b32_e32 v89, v0
	v_mov_b32_e32 v90, v0
	v_mov_b32_e32 v91, v0
	v_mov_b32_e32 v96, v0
	v_mov_b32_e32 v97, v0
	v_mov_b32_e32 v98, v0
	v_mov_b32_e32 v99, v0
	v_mov_b32_e32 v104, v0
	v_mov_b32_e32 v105, v0
	v_mov_b32_e32 v106, v0
	v_mov_b32_e32 v107, v0
	v_mov_b32_e32 v112, v0
	v_mov_b32_e32 v113, v0
	v_mov_b32_e32 v114, v0
	v_mov_b32_e32 v115, v0
	v_mov_b32_e32 v76, v0
	v_mov_b32_e32 v77, v0
	v_mov_b32_e32 v78, v0
	v_mov_b32_e32 v79, v0
	v_mov_b32_e32 v84, v0
	v_mov_b32_e32 v85, v0
	v_mov_b32_e32 v86, v0
	v_mov_b32_e32 v87, v0
	v_mov_b32_e32 v92, v0
	v_mov_b32_e32 v93, v0
	v_mov_b32_e32 v94, v0
	v_mov_b32_e32 v95, v0
	v_mov_b32_e32 v100, v0
	v_mov_b32_e32 v101, v0
	v_mov_b32_e32 v102, v0
	v_mov_b32_e32 v103, v0
	v_mov_b32_e32 v108, v0
	v_mov_b32_e32 v109, v0
	v_mov_b32_e32 v110, v0
	v_mov_b32_e32 v111, v0
	v_mov_b32_e32 v116, v0
	v_mov_b32_e32 v117, v0
	v_mov_b32_e32 v118, v0
	v_mov_b32_e32 v119, v0
	v_mov_b32_e32 v120, v0
	v_mov_b32_e32 v121, v0
	v_mov_b32_e32 v122, v0
	v_mov_b32_e32 v123, v0
	v_mov_b32_e32 v124, v0
	v_mov_b32_e32 v125, v0
	v_mov_b32_e32 v126, v0
	v_mov_b32_e32 v127, v0
	s_barrier
	.p2align	6

.LBB0_206:
	s_andn2_b64 vcc, exec, s[0:1]
	s_cbranch_vccnz .LBB0_149
	v_mov_b32_e32 v20, v224
	s_ashr_i32 s2, s41, 4
	s_lshl_b32 s1, s41, 7
	v_readfirstlane_b32 s31, v20
	s_bfe_u32 s58, s31, 0x20006
	s_lshl_b32 s0, s2, 11
	s_and_b32 s1, s1, 0x780
	s_or_b32 s0, s0, s1
	s_lshl_b32 s1, s58, 5
	v_and_b32_e32 v21, 31, v20
	s_or_b32 s0, s1, s0
	v_or_b32_e32 v160, s0, v21
	s_ashr_i32 s59, s31, 8
	v_ashrrev_i32_e32 v161, 31, v160
	v_lshlrev_b64 v[0:1], 11, v[160:161]
	s_lshl_b32 s0, s59, 6
	v_bfe_u32 v163, v20, 5, 1
	v_lshl_add_u64 v[0:1], s[34:35], 0, v[0:1]
	s_ashr_i32 s1, s0, 31
	v_lshl_add_u64 v[0:1], s[0:1], 1, v[0:1]
	v_lshlrev_b32_e32 v192, 4, v163
	v_lshl_add_u64 v[0:1], v[0:1], 0, v[192:193]
	global_load_dwordx4 v[112:115], v[0:1], off
	global_load_dwordx4 v[116:119], v[0:1], off offset:32
	global_load_dwordx4 v[120:123], v[0:1], off offset:64
	s_lshl_b32 s0, s2, 3
	global_load_dwordx4 v[124:127], v[0:1], off offset:96
	s_or_b32 s0, s0, s54
	s_lshl_b32 s1, s0, 1
	s_mul_i32 s4, s0, 0x90000
	s_mul_hi_i32 s1, s1, 0x48000
	s_add_u32 s2, s56, s4
	s_addc_u32 s3, s57, s1
	s_mul_hi_i32 s0, s0, 0x90000
	s_add_u32 s48, s44, s4
	s_addc_u32 s49, s45, s0
	s_add_u32 s62, s2, 0x48000
	s_addc_u32 s63, s3, 0
	s_add_u32 s4, s48, 0x48000
	s_addc_u32 s5, s49, 0
	s_and_b32 s0, s41, -16
	s_add_i32 s0, s0, s75
	s_add_i32 s0, s0, s59
	s_ashr_i32 s1, s0, 31
	v_ashrrev_i32_e32 v2, 3, v20
	v_and_b32_e32 v3, 7, v20
	s_lshl_b64 s[0:1], s[0:1], 2
	v_readlane_b32 s9, v252, 46
	v_lshlrev_b32_e32 v165, 7, v2
	v_lshlrev_b32_e32 v3, 4, v3
	s_add_u32 s0, s9, s0
	v_readlane_b32 s9, v252, 47
	v_or_b32_e32 v26, v165, v3
	s_addc_u32 s1, s9, s1
	global_load_dwordx4 v[128:131], v26, s[2:3]
	global_load_dwordx4 v[132:135], v26, s[62:63]
	global_load_dword v27, v193, s[0:1]
	v_mul_lo_u32 v2, v2, s7
	v_or_b32_e32 v167, v2, v3
	v_lshrrev_b32_e32 v22, 4, v20
	v_and_b32_e32 v24, 6, v20
	v_bfe_u32 v23, v20, 4, 3
	v_bitop3_b32 v25, v22, v20, 7 bitop3:0x28
	v_lshl_or_b32 v170, v25, 4, v165
	v_lshlrev_b32_e32 v21, 7, v21
	v_mov_b32_e32 v168, 0
	v_mov_b32_e32 v148, 0
	v_and_b32_e32 v166, 63, v20
	s_mov_b32 s64, 0
	v_add_u32_e32 v174, 0, v21
	v_add_u32_e32 v178, 0x4000, v26
	s_mov_b32 s41, 0
	v_mov_b32_e32 v149, v148
	v_mov_b32_e32 v150, v148
	v_mov_b32_e32 v151, v148
	v_mov_b32_e32 v144, v148
	v_mov_b32_e32 v145, v148
	v_mov_b32_e32 v146, v148
	v_mov_b32_e32 v147, v148
	v_mov_b32_e32 v140, v148
	v_mov_b32_e32 v141, v148
	v_mov_b32_e32 v142, v148
	v_mov_b32_e32 v143, v148
	v_mov_b32_e32 v136, v148
	v_mov_b32_e32 v137, v148
	v_mov_b32_e32 v138, v148
	v_mov_b32_e32 v139, v148
	v_mov_b32_e32 v48, 0
	v_mov_b32_e32 v49, v168
	v_mov_b32_e32 v50, v168
	v_mov_b32_e32 v51, v168
	v_mov_b32_e32 v52, v168
	v_mov_b32_e32 v53, v168
	v_mov_b32_e32 v54, v168
	v_mov_b32_e32 v55, v168
	v_mov_b32_e32 v56, v168
	v_mov_b32_e32 v57, v168
	v_mov_b32_e32 v58, v168
	v_mov_b32_e32 v59, v168
	v_mov_b32_e32 v60, v168
	v_mov_b32_e32 v61, v168
	v_mov_b32_e32 v62, v168
	v_mov_b32_e32 v63, v168
	s_waitcnt vmcnt(0)
	v_and_b32_e32 v1, 0xffff0000, v112
	v_and_b32_e32 v3, 0xffff0000, v113
	v_lshlrev_b32_e32 v0, 16, v112
	v_lshlrev_b32_e32 v2, 16, v113
	v_and_b32_e32 v5, 0xffff0000, v114
	v_mul_f32_e32 v1, v1, v1
	v_mul_f32_e32 v3, v3, v3
	v_lshlrev_b32_e32 v4, 16, v114
	v_and_b32_e32 v7, 0xffff0000, v115
	v_mul_f32_e32 v5, v5, v5
	v_fmac_f32_e32 v1, v0, v0
	v_fmac_f32_e32 v3, v2, v2
	v_lshlrev_b32_e32 v6, 16, v115
	v_and_b32_e32 v9, 0xffff0000, v116
	v_mul_f32_e32 v7, v7, v7
	v_fmac_f32_e32 v5, v4, v4
	v_add_f32_e32 v0, v1, v3
	v_lshlrev_b32_e32 v8, 16, v116
	v_and_b32_e32 v11, 0xffff0000, v117
	v_mul_f32_e32 v9, v9, v9
	v_fmac_f32_e32 v7, v6, v6
	v_add_f32_e32 v0, v5, v0
	v_lshlrev_b32_e32 v10, 16, v117
	v_and_b32_e32 v13, 0xffff0000, v118
	v_mul_f32_e32 v11, v11, v11
	v_fmac_f32_e32 v9, v8, v8
	v_add_f32_e32 v0, v7, v0
	v_lshlrev_b32_e32 v12, 16, v118
	v_and_b32_e32 v15, 0xffff0000, v119
	v_mul_f32_e32 v13, v13, v13
	v_fmac_f32_e32 v11, v10, v10
	v_add_f32_e32 v0, v9, v0
	v_lshlrev_b32_e32 v14, 16, v119
	v_mul_f32_e32 v15, v15, v15
	v_fmac_f32_e32 v13, v12, v12
	v_add_f32_e32 v0, v11, v0
	v_fmac_f32_e32 v15, v14, v14
	v_add_f32_e32 v0, v13, v0
	v_add_f32_e32 v17, v15, v0
	global_load_dwordx4 v[0:3], v167, s[48:49]
	global_load_dwordx4 v[4:7], v167, s[4:5]
	v_add_u32_e32 v12, 0x2000, v26
	global_load_dwordx4 v[8:11], v12, s[2:3]
	s_nop 0
	global_load_dwordx4 v[12:15], v12, s[62:63]
	v_and_b32_e32 v18, 0xffff0000, v120
	v_lshlrev_b32_e32 v16, 16, v120
	v_mul_f32_e32 v18, v18, v18
	v_fmac_f32_e32 v18, v16, v16
	v_add_f32_e32 v16, v18, v17
	v_and_b32_e32 v18, 0xffff0000, v121
	v_lshlrev_b32_e32 v17, 16, v121
	v_mul_f32_e32 v18, v18, v18
	v_fmac_f32_e32 v18, v17, v17
	v_add_f32_e32 v28, v18, v16
	v_and_b32_e32 v19, 0xffff0000, v123
	v_and_b32_e32 v18, 0xffff0000, v122
	v_lshlrev_b32_e32 v17, 16, v123
	v_lshlrev_b32_e32 v16, 16, v122
	v_pk_mul_f32 v[18:19], v[18:19], v[18:19]
	v_mov_b32_e32 v32, 0
	v_pk_fma_f32 v[16:17], v[16:17], v[16:17], v[18:19]
	v_and_b32_e32 v19, 0xffff0000, v125
	v_add_f32_e32 v16, v16, v28
	v_and_b32_e32 v18, 0xffff0000, v124
	v_add_f32_e32 v28, v17, v16
	v_lshlrev_b32_e32 v17, 16, v125
	v_lshlrev_b32_e32 v16, 16, v124
	v_pk_mul_f32 v[18:19], v[18:19], v[18:19]
	v_mov_b32_e32 v33, v168
	v_pk_fma_f32 v[16:17], v[16:17], v[16:17], v[18:19]
	v_and_b32_e32 v19, 0xffff0000, v127
	v_add_f32_e32 v16, v16, v28
	v_and_b32_e32 v18, 0xffff0000, v126
	v_add_f32_e32 v28, v17, v16
	v_lshlrev_b32_e32 v17, 16, v127
	v_lshlrev_b32_e32 v16, 16, v126
	v_pk_mul_f32 v[18:19], v[18:19], v[18:19]
	v_mov_b32_e32 v34, v168
	v_pk_fma_f32 v[16:17], v[16:17], v[16:17], v[18:19]
	v_and_b32_e32 v18, 64, v229
	v_add_f32_e32 v16, v16, v28
	v_add_f32_e32 v16, v17, v16
	v_xor_b32_e32 v17, 32, v229
	v_add_u32_e32 v18, 64, v18
	v_cmp_lt_i32_e32 vcc, v17, v18
	v_lshlrev_b32_e32 v19, 3, v20
	v_bitop3_b32 v18, v22, v24, 7 bitop3:0x6c
	v_cndmask_b32_e32 v17, v229, v17, vcc
	v_lshlrev_b32_e32 v164, 2, v17
	ds_bpermute_b32 v17, v164, v16
	v_and_b32_e32 v19, 8, v19
	v_bitop3_b32 v22, v24, v23, 1 bitop3:0x36
	v_lshl_or_b32 v172, v18, 4, v19
	v_lshl_or_b32 v169, v22, 4, v19
	s_waitcnt lgkmcnt(0)
	v_add_f32_e32 v16, v16, v17
	v_mul_f32_e32 v16, v27, v16
	v_mul_f32_e32 v17, 0x4f800000, v16
	v_cmp_gt_f32_e32 vcc, s92, v16
	v_mov_b32_e32 v35, v168
	v_mov_b32_e32 v36, v168
	v_cndmask_b32_e32 v16, v16, v17, vcc
	v_sqrt_f32_e32 v17, v16
	v_mov_b32_e32 v37, v168
	v_mov_b32_e32 v38, v168
	v_mov_b32_e32 v39, v168
	v_add_u32_e32 v18, -1, v17
	v_fma_f32 v19, -v18, v17, v16
	v_cmp_ge_f32_e64 s[0:1], 0, v19
	v_add_u32_e32 v19, 1, v17
	v_mov_b32_e32 v40, v168
	v_cndmask_b32_e64 v18, v17, v18, s[0:1]
	v_fma_f32 v17, -v19, v17, v16
	v_cmp_lt_f32_e64 s[0:1], 0, v17
	v_mov_b32_e32 v41, v168
	v_mov_b32_e32 v42, v168
	v_cndmask_b32_e64 v17, v18, v19, s[0:1]
	v_mul_f32_e32 v18, 0x37800000, v17
	v_cndmask_b32_e32 v17, v17, v18, vcc
	v_cmp_class_f32_e32 vcc, v16, v228
	v_add_u32_e32 v18, 0, v165
	v_add_u32_e32 v19, v18, v172
	v_cndmask_b32_e32 v16, v17, v16, vcc
	v_fmamk_f32 v16, v16, 0x3f828f5c, v227
	v_add_u32_e32 v17, 0, v170
	v_xor_b32_e32 v64, 0x80000000, v16
	v_lshrrev_b32_e32 v16, 1, v20
	s_lshl_b32 s0, s59, 13
	ds_write_b128 v17, v[128:131]
	ds_write_b128 v17, v[132:135] offset:8192
	s_waitcnt vmcnt(3)
	ds_write_b64 v19, v[0:1] offset:49152
	v_add_u32_e32 v0, v18, v169
	s_waitcnt vmcnt(2)
	ds_write_b64 v19, v[4:5] offset:57344
	ds_write2st64_b64 v0, v[2:3], v[6:7] offset0:96 offset1:112
	s_waitcnt vmcnt(1)
	ds_write_b128 v17, v[8:11] offset:16384
	s_waitcnt vmcnt(0)
	ds_write_b128 v17, v[12:15] offset:24576
	s_add_i32 s0, s0, 0
	v_bitop3_b32 v0, v163, v16, 7 bitop3:0x78
	v_add_u32_e32 v177, s0, v21
	v_lshlrev_b32_e32 v176, 4, v0
	v_add_u32_e32 v4, v177, v176
	s_waitcnt lgkmcnt(0)
	s_barrier
	ds_read_b128 v[0:3], v4
	ds_read_b128 v[4:7], v4 offset:4096
	v_mov_b32_e32 v65, v64
	v_mov_b32_e32 v66, v64
	v_mov_b32_e32 v67, v64
	v_mov_b32_e32 v68, v64
	v_mov_b32_e32 v69, v64
	v_mov_b32_e32 v70, v64
	v_mov_b32_e32 v71, v64
	v_mov_b32_e32 v72, v64
	v_mov_b32_e32 v73, v64
	v_mov_b32_e32 v74, v64
	v_mov_b32_e32 v75, v64
	v_mov_b32_e32 v76, v64
	v_mov_b32_e32 v77, v64
	v_mov_b32_e32 v78, v64
	v_mov_b32_e32 v79, v64
	v_bfe_u32 v16, v20, 1, 3
	v_mov_b32_e32 v43, v168
	s_waitcnt lgkmcnt(1)
	v_mfma_f32_32x32x16_bf16 v[96:111], v[0:3], v[112:115], v[64:79]
	v_bitop3_b32 v0, v163, v16, 2 bitop3:0x36
	v_lshlrev_b32_e32 v175, 4, v0
	v_add_u32_e32 v8, v177, v175
	ds_read_b128 v[0:3], v8
	ds_read_b128 v[8:11], v8 offset:4096
	v_mov_b32_e32 v44, v168
	v_mov_b32_e32 v45, v168
	v_mov_b32_e32 v46, v168
	s_waitcnt lgkmcnt(2)
	v_mfma_f32_32x32x16_bf16 v[80:95], v[4:7], v[112:115], v[64:79]
	v_mov_b32_e32 v47, v168
	v_mov_b32_e32 v20, v168
	v_mov_b32_e32 v21, v168
	v_mov_b32_e32 v22, v168
	v_mov_b32_e32 v23, v168
	v_mov_b32_e32 v24, v168
	v_mov_b32_e32 v25, v168
	s_waitcnt lgkmcnt(1)
	v_mfma_f32_32x32x16_bf16 v[96:111], v[0:3], v[116:119], v[96:111]
	v_bitop3_b32 v0, v163, v16, 4 bitop3:0x36
	v_lshlrev_b32_e32 v173, 4, v0
	v_add_u32_e32 v12, v177, v173
	ds_read_b128 v[0:3], v12
	ds_read_b128 v[12:15], v12 offset:4096
	v_mov_b32_e32 v26, v168
	v_mov_b32_e32 v27, v168
	v_mov_b32_e32 v28, v168
	s_waitcnt lgkmcnt(2)
	v_mfma_f32_32x32x16_bf16 v[80:95], v[8:11], v[116:119], v[80:95]
	v_mov_b32_e32 v29, v168
	v_mov_b32_e32 v30, v168
	v_mov_b32_e32 v31, v168
	v_mov_b32_e32 v4, v168
	v_mov_b32_e32 v5, v168
	v_mov_b32_e32 v6, v168
	v_mov_b32_e32 v7, v168
	s_waitcnt lgkmcnt(1)
	v_mfma_f32_32x32x16_bf16 v[96:111], v[0:3], v[120:123], v[96:111]
	v_bitop3_b32 v0, v163, v16, 6 bitop3:0x36
	v_lshlrev_b32_e32 v171, 4, v0
	v_add_u32_e32 v16, v177, v171
	ds_read_b128 v[0:3], v16
	ds_read_b128 v[16:19], v16 offset:4096
	v_mov_b32_e32 v8, v168
	v_mov_b32_e32 v9, v168
	v_mov_b32_e32 v10, v168
	s_waitcnt lgkmcnt(2)
	v_mfma_f32_32x32x16_bf16 v[80:95], v[12:15], v[120:123], v[80:95]
	v_mov_b32_e32 v11, v168
	v_mov_b32_e32 v12, v168
	v_mov_b32_e32 v13, v168
	v_mov_b32_e32 v14, v168
	v_mov_b32_e32 v15, v168
	s_waitcnt lgkmcnt(1)
	v_mfma_f32_32x32x16_bf16 v[96:111], v[0:3], v[124:127], v[96:111]
	v_mov_b32_e32 v0, 0
	v_mov_b32_e32 v1, v168
	v_mov_b32_e32 v2, v168
	v_mov_b32_e32 v3, v168
	s_waitcnt lgkmcnt(0)
	v_mfma_f32_32x32x16_bf16 v[80:95], v[16:19], v[124:127], v[80:95]
	v_mov_b32_e32 v16, 0
	v_mov_b32_e32 v17, v168
	v_mov_b32_e32 v18, v168
	v_mov_b32_e32 v19, v168
	.p2align	6

.LBB0_241:
	s_add_i32 s64, s71, -2
	s_add_u32 s2, s2, 0x200080
	s_addc_u32 s3, s3, 0
	s_add_u32 s75, s4, 0x100
	v_mov_b32_e32 v0, 0
	s_addc_u32 s78, s5, 0
	s_mov_b32 s4, 0
	v_mov_b32_e32 v1, v0
	v_mov_b32_e32 v2, v0
	v_mov_b32_e32 v3, v0
	v_mov_b32_e32 v4, v0
	v_mov_b32_e32 v5, v0
	v_mov_b32_e32 v6, v0
	v_mov_b32_e32 v7, v0
	v_mov_b32_e32 v8, v0
	v_mov_b32_e32 v9, v0
	v_mov_b32_e32 v10, v0
	v_mov_b32_e32 v11, v0
	v_mov_b32_e32 v16, v0
	v_mov_b32_e32 v17, v0
	v_mov_b32_e32 v18, v0
	v_mov_b32_e32 v19, v0
	v_mov_b32_e32 v24, v0
	v_mov_b32_e32 v25, v0
	v_mov_b32_e32 v26, v0
	v_mov_b32_e32 v27, v0
	v_mov_b32_e32 v32, v0
	v_mov_b32_e32 v33, v0
	v_mov_b32_e32 v34, v0
	v_mov_b32_e32 v35, v0
	v_mov_b32_e32 v40, v0
	v_mov_b32_e32 v41, v0
	v_mov_b32_e32 v42, v0
	v_mov_b32_e32 v43, v0
	v_mov_b32_e32 v48, v0
	v_mov_b32_e32 v49, v0
	v_mov_b32_e32 v50, v0
	v_mov_b32_e32 v51, v0
	v_mov_b32_e32 v12, v0
	v_mov_b32_e32 v13, v0
	v_mov_b32_e32 v14, v0
	v_mov_b32_e32 v15, v0
	v_mov_b32_e32 v20, v0
	v_mov_b32_e32 v21, v0
	v_mov_b32_e32 v22, v0
	v_mov_b32_e32 v23, v0
	v_mov_b32_e32 v28, v0
	v_mov_b32_e32 v29, v0
	v_mov_b32_e32 v30, v0
	v_mov_b32_e32 v31, v0
	v_mov_b32_e32 v36, v0
	v_mov_b32_e32 v37, v0
	v_mov_b32_e32 v38, v0
	v_mov_b32_e32 v39, v0
	v_mov_b32_e32 v44, v0
	v_mov_b32_e32 v45, v0
	v_mov_b32_e32 v46, v0
	v_mov_b32_e32 v47, v0
	v_mov_b32_e32 v52, v0
	v_mov_b32_e32 v53, v0
	v_mov_b32_e32 v54, v0
	v_mov_b32_e32 v55, v0
	v_mov_b32_e32 v56, v0
	v_mov_b32_e32 v57, v0
	v_mov_b32_e32 v58, v0
	v_mov_b32_e32 v59, v0
	v_mov_b32_e32 v60, v0
	v_mov_b32_e32 v61, v0
	v_mov_b32_e32 v62, v0
	v_mov_b32_e32 v63, v0
	v_mov_b32_e32 v64, v0
	v_mov_b32_e32 v65, v0
	v_mov_b32_e32 v66, v0
	v_mov_b32_e32 v67, v0
	v_mov_b32_e32 v68, v0
	v_mov_b32_e32 v69, v0
	v_mov_b32_e32 v70, v0
	v_mov_b32_e32 v71, v0
	v_mov_b32_e32 v72, v0
	v_mov_b32_e32 v73, v0
	v_mov_b32_e32 v74, v0
	v_mov_b32_e32 v75, v0
	v_mov_b32_e32 v80, v0
	v_mov_b32_e32 v81, v0
	v_mov_b32_e32 v82, v0
	v_mov_b32_e32 v83, v0
	v_mov_b32_e32 v88, v0
	v_mov_b32_e32 v89, v0
	v_mov_b32_e32 v90, v0
	v_mov_b32_e32 v91, v0
	v_mov_b32_e32 v96, v0
	v_mov_b32_e32 v97, v0
	v_mov_b32_e32 v98, v0
	v_mov_b32_e32 v99, v0
	v_mov_b32_e32 v104, v0
	v_mov_b32_e32 v105, v0
	v_mov_b32_e32 v106, v0
	v_mov_b32_e32 v107, v0
	v_mov_b32_e32 v112, v0
	v_mov_b32_e32 v113, v0
	v_mov_b32_e32 v114, v0
	v_mov_b32_e32 v115, v0
	v_mov_b32_e32 v76, v0
	v_mov_b32_e32 v77, v0
	v_mov_b32_e32 v78, v0
	v_mov_b32_e32 v79, v0
	v_mov_b32_e32 v84, v0
	v_mov_b32_e32 v85, v0
	v_mov_b32_e32 v86, v0
	v_mov_b32_e32 v87, v0
	v_mov_b32_e32 v92, v0
	v_mov_b32_e32 v93, v0
	v_mov_b32_e32 v94, v0
	v_mov_b32_e32 v95, v0
	v_mov_b32_e32 v100, v0
	v_mov_b32_e32 v101, v0
	v_mov_b32_e32 v102, v0
	v_mov_b32_e32 v103, v0
	v_mov_b32_e32 v108, v0
	v_mov_b32_e32 v109, v0
	v_mov_b32_e32 v110, v0
	v_mov_b32_e32 v111, v0
	v_mov_b32_e32 v116, v0
	v_mov_b32_e32 v117, v0
	v_mov_b32_e32 v118, v0
	v_mov_b32_e32 v119, v0
	v_mov_b32_e32 v120, v0
	v_mov_b32_e32 v121, v0
	v_mov_b32_e32 v122, v0
	v_mov_b32_e32 v123, v0
	v_mov_b32_e32 v124, v0
	v_mov_b32_e32 v125, v0
	v_mov_b32_e32 v126, v0
	v_mov_b32_e32 v127, v0
	.p2align	6

.LBB0_255:
	s_add_u32 s2, s2, 0x80080
	s_addc_u32 s3, s3, 0
	s_add_u32 s15, s4, 0x100
	v_mov_b32_e32 v0, 0
	s_addc_u32 s29, s5, 0
	s_mov_b32 s69, -2
	v_mov_b32_e32 v1, v0
	v_mov_b32_e32 v2, v0
	v_mov_b32_e32 v3, v0
	v_mov_b32_e32 v4, v0
	v_mov_b32_e32 v5, v0
	v_mov_b32_e32 v6, v0
	v_mov_b32_e32 v7, v0
	v_mov_b32_e32 v16, v0
	v_mov_b32_e32 v17, v0
	v_mov_b32_e32 v18, v0
	v_mov_b32_e32 v19, v0
	v_mov_b32_e32 v20, v0
	v_mov_b32_e32 v21, v0
	v_mov_b32_e32 v22, v0
	v_mov_b32_e32 v23, v0
	v_mov_b32_e32 v32, v0
	v_mov_b32_e32 v33, v0
	v_mov_b32_e32 v34, v0
	v_mov_b32_e32 v35, v0
	v_mov_b32_e32 v36, v0
	v_mov_b32_e32 v37, v0
	v_mov_b32_e32 v38, v0
	v_mov_b32_e32 v39, v0
	v_mov_b32_e32 v48, v0
	v_mov_b32_e32 v49, v0
	v_mov_b32_e32 v50, v0
	v_mov_b32_e32 v51, v0
	v_mov_b32_e32 v52, v0
	v_mov_b32_e32 v53, v0
	v_mov_b32_e32 v54, v0
	v_mov_b32_e32 v55, v0
	v_mov_b32_e32 v8, v0
	v_mov_b32_e32 v9, v0
	v_mov_b32_e32 v10, v0
	v_mov_b32_e32 v11, v0
	v_mov_b32_e32 v12, v0
	v_mov_b32_e32 v13, v0
	v_mov_b32_e32 v14, v0
	v_mov_b32_e32 v15, v0
	v_mov_b32_e32 v24, v0
	v_mov_b32_e32 v25, v0
	v_mov_b32_e32 v26, v0
	v_mov_b32_e32 v27, v0
	v_mov_b32_e32 v28, v0
	v_mov_b32_e32 v29, v0
	v_mov_b32_e32 v30, v0
	v_mov_b32_e32 v31, v0
	v_mov_b32_e32 v40, v0
	v_mov_b32_e32 v41, v0
	v_mov_b32_e32 v42, v0
	v_mov_b32_e32 v43, v0
	v_mov_b32_e32 v44, v0
	v_mov_b32_e32 v45, v0
	v_mov_b32_e32 v46, v0
	v_mov_b32_e32 v47, v0
	v_mov_b32_e32 v56, v0
	v_mov_b32_e32 v57, v0
	v_mov_b32_e32 v58, v0
	v_mov_b32_e32 v59, v0
	v_mov_b32_e32 v60, v0
	v_mov_b32_e32 v61, v0
	v_mov_b32_e32 v62, v0
	v_mov_b32_e32 v63, v0
	v_mov_b32_e32 v64, v0
	v_mov_b32_e32 v65, v0
	v_mov_b32_e32 v66, v0
	v_mov_b32_e32 v67, v0
	v_mov_b32_e32 v68, v0
	v_mov_b32_e32 v69, v0
	v_mov_b32_e32 v70, v0
	v_mov_b32_e32 v71, v0
	v_mov_b32_e32 v80, v0
	v_mov_b32_e32 v81, v0
	v_mov_b32_e32 v82, v0
	v_mov_b32_e32 v83, v0
	v_mov_b32_e32 v84, v0
	v_mov_b32_e32 v85, v0
	v_mov_b32_e32 v86, v0
	v_mov_b32_e32 v87, v0
	v_mov_b32_e32 v96, v0
	v_mov_b32_e32 v97, v0
	v_mov_b32_e32 v98, v0
	v_mov_b32_e32 v99, v0
	v_mov_b32_e32 v100, v0
	v_mov_b32_e32 v101, v0
	v_mov_b32_e32 v102, v0
	v_mov_b32_e32 v103, v0
	v_mov_b32_e32 v112, v0
	v_mov_b32_e32 v113, v0
	v_mov_b32_e32 v114, v0
	v_mov_b32_e32 v115, v0
	v_mov_b32_e32 v116, v0
	v_mov_b32_e32 v117, v0
	v_mov_b32_e32 v118, v0
	v_mov_b32_e32 v119, v0
	v_mov_b32_e32 v72, v0
	v_mov_b32_e32 v73, v0
	v_mov_b32_e32 v74, v0
	v_mov_b32_e32 v75, v0
	v_mov_b32_e32 v76, v0
	v_mov_b32_e32 v77, v0
	v_mov_b32_e32 v78, v0
	v_mov_b32_e32 v79, v0
	v_mov_b32_e32 v88, v0
	v_mov_b32_e32 v89, v0
	v_mov_b32_e32 v90, v0
	v_mov_b32_e32 v91, v0
	v_mov_b32_e32 v92, v0
	v_mov_b32_e32 v93, v0
	v_mov_b32_e32 v94, v0
	v_mov_b32_e32 v95, v0
	v_mov_b32_e32 v104, v0
	v_mov_b32_e32 v105, v0
	v_mov_b32_e32 v106, v0
	v_mov_b32_e32 v107, v0
	v_mov_b32_e32 v108, v0
	v_mov_b32_e32 v109, v0
	v_mov_b32_e32 v110, v0
	v_mov_b32_e32 v111, v0
	v_mov_b32_e32 v120, v0
	v_mov_b32_e32 v121, v0
	v_mov_b32_e32 v122, v0
	v_mov_b32_e32 v123, v0
	v_mov_b32_e32 v124, v0
	v_mov_b32_e32 v125, v0
	v_mov_b32_e32 v126, v0
	v_mov_b32_e32 v127, v0
	.p2align	6

.LBB0_328:
	s_add_u32 s0, s4, 0x80080
	s_addc_u32 s1, s5, 0
	s_add_u32 s36, s2, 0x100
	v_mov_b32_e32 v0, 0
	s_addc_u32 s37, s3, 0
	s_mov_b32 s40, -2
	v_mov_b32_e32 v1, v0
	v_mov_b32_e32 v2, v0
	v_mov_b32_e32 v3, v0
	v_mov_b32_e32 v4, v0
	v_mov_b32_e32 v5, v0
	v_mov_b32_e32 v6, v0
	v_mov_b32_e32 v7, v0
	v_mov_b32_e32 v16, v0
	v_mov_b32_e32 v17, v0
	v_mov_b32_e32 v18, v0
	v_mov_b32_e32 v19, v0
	v_mov_b32_e32 v20, v0
	v_mov_b32_e32 v21, v0
	v_mov_b32_e32 v22, v0
	v_mov_b32_e32 v23, v0
	v_mov_b32_e32 v32, v0
	v_mov_b32_e32 v33, v0
	v_mov_b32_e32 v34, v0
	v_mov_b32_e32 v35, v0
	v_mov_b32_e32 v36, v0
	v_mov_b32_e32 v37, v0
	v_mov_b32_e32 v38, v0
	v_mov_b32_e32 v39, v0
	v_mov_b32_e32 v48, v0
	v_mov_b32_e32 v49, v0
	v_mov_b32_e32 v50, v0
	v_mov_b32_e32 v51, v0
	v_mov_b32_e32 v52, v0
	v_mov_b32_e32 v53, v0
	v_mov_b32_e32 v54, v0
	v_mov_b32_e32 v55, v0
	v_mov_b32_e32 v8, v0
	v_mov_b32_e32 v9, v0
	v_mov_b32_e32 v10, v0
	v_mov_b32_e32 v11, v0
	v_mov_b32_e32 v12, v0
	v_mov_b32_e32 v13, v0
	v_mov_b32_e32 v14, v0
	v_mov_b32_e32 v15, v0
	v_mov_b32_e32 v24, v0
	v_mov_b32_e32 v25, v0
	v_mov_b32_e32 v26, v0
	v_mov_b32_e32 v27, v0
	v_mov_b32_e32 v28, v0
	v_mov_b32_e32 v29, v0
	v_mov_b32_e32 v30, v0
	v_mov_b32_e32 v31, v0
	v_mov_b32_e32 v40, v0
	v_mov_b32_e32 v41, v0
	v_mov_b32_e32 v42, v0
	v_mov_b32_e32 v43, v0
	v_mov_b32_e32 v44, v0
	v_mov_b32_e32 v45, v0
	v_mov_b32_e32 v46, v0
	v_mov_b32_e32 v47, v0
	v_mov_b32_e32 v56, v0
	v_mov_b32_e32 v57, v0
	v_mov_b32_e32 v58, v0
	v_mov_b32_e32 v59, v0
	v_mov_b32_e32 v60, v0
	v_mov_b32_e32 v61, v0
	v_mov_b32_e32 v62, v0
	v_mov_b32_e32 v63, v0
	v_mov_b32_e32 v64, v0
	v_mov_b32_e32 v65, v0
	v_mov_b32_e32 v66, v0
	v_mov_b32_e32 v67, v0
	v_mov_b32_e32 v68, v0
	v_mov_b32_e32 v69, v0
	v_mov_b32_e32 v70, v0
	v_mov_b32_e32 v71, v0
	v_mov_b32_e32 v80, v0
	v_mov_b32_e32 v81, v0
	v_mov_b32_e32 v82, v0
	v_mov_b32_e32 v83, v0
	v_mov_b32_e32 v84, v0
	v_mov_b32_e32 v85, v0
	v_mov_b32_e32 v86, v0
	v_mov_b32_e32 v87, v0
	v_mov_b32_e32 v96, v0
	v_mov_b32_e32 v97, v0
	v_mov_b32_e32 v98, v0
	v_mov_b32_e32 v99, v0
	v_mov_b32_e32 v100, v0
	v_mov_b32_e32 v101, v0
	v_mov_b32_e32 v102, v0
	v_mov_b32_e32 v103, v0
	v_mov_b32_e32 v112, v0
	v_mov_b32_e32 v113, v0
	v_mov_b32_e32 v114, v0
	v_mov_b32_e32 v115, v0
	v_mov_b32_e32 v116, v0
	v_mov_b32_e32 v117, v0
	v_mov_b32_e32 v118, v0
	v_mov_b32_e32 v119, v0
	v_mov_b32_e32 v72, v0
	v_mov_b32_e32 v73, v0
	v_mov_b32_e32 v74, v0
	v_mov_b32_e32 v75, v0
	v_mov_b32_e32 v76, v0
	v_mov_b32_e32 v77, v0
	v_mov_b32_e32 v78, v0
	v_mov_b32_e32 v79, v0
	v_mov_b32_e32 v88, v0
	v_mov_b32_e32 v89, v0
	v_mov_b32_e32 v90, v0
	v_mov_b32_e32 v91, v0
	v_mov_b32_e32 v92, v0
	v_mov_b32_e32 v93, v0
	v_mov_b32_e32 v94, v0
	v_mov_b32_e32 v95, v0
	v_mov_b32_e32 v104, v0
	v_mov_b32_e32 v105, v0
	v_mov_b32_e32 v106, v0
	v_mov_b32_e32 v107, v0
	v_mov_b32_e32 v108, v0
	v_mov_b32_e32 v109, v0
	v_mov_b32_e32 v110, v0
	v_mov_b32_e32 v111, v0
	v_mov_b32_e32 v120, v0
	v_mov_b32_e32 v121, v0
	v_mov_b32_e32 v122, v0
	v_mov_b32_e32 v123, v0
	v_mov_b32_e32 v124, v0
	v_mov_b32_e32 v125, v0
	v_mov_b32_e32 v126, v0
	v_mov_b32_e32 v127, v0
	.p2align	6
